# GU/DN phase ends: LDS-DMA drain counted (vmcnt 8 / 16) so the last epilogue's stores stay in flight under the weight-conversion block (on v16)
# baseline (speedup 1.0000x reference)
.LBB0_232:
	ds_read_b128 v[158:161], v152
	ds_read_b128 v[162:165], v152 offset:1024
	ds_read_b128 v[166:169], v152 offset:2048
	ds_read_b128 v[170:173], v152 offset:3072
	s_mov_b32 m0, s47
	v_lshl_add_u64 v[206:207], v[142:143], 0, s[34:35]
	ds_read_b128 v[174:177], v153
	ds_read_b128 v[178:181], v153 offset:1024
	ds_read_b128 v[182:185], v153 offset:2048
	ds_read_b128 v[186:189], v153 offset:3072
	ds_read_b128 v[190:193], v153 offset:4096
	ds_read_b128 v[194:197], v153 offset:5120
	ds_read_b128 v[198:201], v153 offset:6144
	ds_read_b128 v[202:205], v153 offset:7168
	global_load_lds_dwordx4 v[206:207], off
	s_mov_b32 m0, s48
	v_lshl_add_u64 v[206:207], v[144:145], 0, s[34:35]
	global_load_lds_dwordx4 v[206:207], off
	s_waitcnt lgkmcnt(8)
	s_barrier
	s_waitcnt lgkmcnt(0)
	v_mfma_f32_16x16x32_bf16 v[120:123], v[158:161], v[174:177], v[120:123]
	s_add_i32 s61, s34, 0xfffc0080
	v_mfma_f32_16x16x32_bf16 v[112:115], v[166:169], v[174:177], v[112:115]
	s_cmp_eq_u32 s19, 12
	v_mfma_f32_16x16x32_bf16 v[104:107], v[158:161], v[182:185], v[104:107]
	s_cselect_b64 s[36:37], -1, 0
	v_mfma_f32_16x16x32_bf16 v[96:99], v[166:169], v[182:185], v[96:99]
	s_and_b64 s[62:63], s[36:37], exec
	v_mfma_f32_16x16x32_bf16 v[88:91], v[158:161], v[190:193], v[88:91]
	s_cselect_b32 s61, 0, s61
	v_mfma_f32_16x16x32_bf16 v[80:83], v[166:169], v[190:193], v[80:83]
	s_and_b64 s[36:37], s[30:31], s[36:37]
	v_mfma_f32_16x16x32_bf16 v[72:75], v[158:161], v[198:201], v[72:75]
	s_and_b64 s[36:37], s[36:37], exec
	v_mfma_f32_16x16x32_bf16 v[60:63], v[166:169], v[198:201], v[60:63]
	s_cselect_b32 s63, s21, s27
	v_mfma_f32_16x16x32_bf16 v[120:123], v[162:165], v[178:181], v[120:123]
	s_cselect_b32 s62, s20, s26
	v_mfma_f32_16x16x32_bf16 v[112:115], v[170:173], v[178:181], v[112:115]
	s_cselect_b32 s37, s23, s29
	v_mfma_f32_16x16x32_bf16 v[104:107], v[162:165], v[186:189], v[104:107]
	s_cselect_b32 s36, s22, s28
	v_mfma_f32_16x16x32_bf16 v[96:99], v[170:173], v[186:189], v[96:99]
	v_mfma_f32_16x16x32_bf16 v[88:91], v[162:165], v[194:197], v[88:91]
	v_mfma_f32_16x16x32_bf16 v[80:83], v[170:173], v[194:197], v[80:83]
	v_mfma_f32_16x16x32_bf16 v[72:75], v[162:165], v[202:205], v[72:75]
	v_mfma_f32_16x16x32_bf16 v[60:63], v[170:173], v[202:205], v[60:63]
	s_barrier
	s_add_u32 s36, s36, s61
	s_addc_u32 s37, s37, 0
	s_mov_b32 m0, s49
	v_lshl_add_u64 v[218:219], s[36:37], 0, v[134:135]
	ds_read_b128 v[206:209], v154
	ds_read_b128 v[210:213], v154 offset:1024
	ds_read_b128 v[214:217], v154 offset:2048
	ds_read_b128 v[222:225], v154 offset:3072
	global_load_lds_dwordx4 v[218:219], off
	s_mov_b32 m0, s50
	v_lshl_add_u64 v[226:227], s[36:37], 0, v[130:131]
	global_load_lds_dwordx4 v[226:227], off
	s_barrier
	s_waitcnt lgkmcnt(0)
	v_mfma_f32_16x16x32_bf16 v[124:127], v[206:209], v[174:177], v[124:127]
	v_mfma_f32_16x16x32_bf16 v[116:119], v[214:217], v[174:177], v[116:119]
	v_mfma_f32_16x16x32_bf16 v[108:111], v[206:209], v[182:185], v[108:111]
	v_mfma_f32_16x16x32_bf16 v[100:103], v[214:217], v[182:185], v[100:103]
	v_mfma_f32_16x16x32_bf16 v[92:95], v[206:209], v[190:193], v[92:95]
	v_mfma_f32_16x16x32_bf16 v[84:87], v[214:217], v[190:193], v[84:87]
	v_mfma_f32_16x16x32_bf16 v[76:79], v[206:209], v[198:201], v[76:79]
	v_mfma_f32_16x16x32_bf16 v[64:67], v[214:217], v[198:201], v[64:67]
	v_mfma_f32_16x16x32_bf16 v[124:127], v[210:213], v[178:181], v[124:127]
	v_mfma_f32_16x16x32_bf16 v[116:119], v[222:225], v[178:181], v[116:119]
	v_mfma_f32_16x16x32_bf16 v[108:111], v[210:213], v[186:189], v[108:111]
	v_mfma_f32_16x16x32_bf16 v[100:103], v[222:225], v[186:189], v[100:103]
	v_mfma_f32_16x16x32_bf16 v[92:95], v[210:213], v[194:197], v[92:95]
	v_mfma_f32_16x16x32_bf16 v[84:87], v[222:225], v[194:197], v[84:87]
	v_mfma_f32_16x16x32_bf16 v[76:79], v[210:213], v[202:205], v[76:79]
	v_mfma_f32_16x16x32_bf16 v[64:67], v[222:225], v[202:205], v[64:67]
	s_add_u32 s62, s62, s61
	s_addc_u32 s63, s63, 0
	s_mov_b32 m0, s25
	v_lshl_add_u64 v[228:229], s[62:63], 0, v[136:137]
	s_barrier
	ds_read_b128 v[174:177], v153 offset:16384
	ds_read_b128 v[178:181], v153 offset:17408
	ds_read_b128 v[182:185], v153 offset:18432
	ds_read_b128 v[186:189], v153 offset:19456
	ds_read_b128 v[190:193], v153 offset:20480
	ds_read_b128 v[194:197], v153 offset:21504
	ds_read_b128 v[198:201], v153 offset:22528
	ds_read_b128 v[202:205], v153 offset:23552
	global_load_lds_dwordx4 v[228:229], off
	s_mov_b32 m0, s41
	v_lshl_add_u64 v[230:231], s[62:63], 0, v[132:133]
	global_load_lds_dwordx4 v[230:231], off
	s_barrier
	s_waitcnt lgkmcnt(0)
	v_mfma_f32_16x16x32_bf16 v[56:59], v[158:161], v[174:177], v[56:59]
	v_mfma_f32_16x16x32_bf16 v[48:51], v[166:169], v[174:177], v[48:51]
	v_mfma_f32_16x16x32_bf16 v[40:43], v[158:161], v[182:185], v[40:43]
	v_mfma_f32_16x16x32_bf16 v[32:35], v[166:169], v[182:185], v[32:35]
	v_mfma_f32_16x16x32_bf16 v[24:27], v[158:161], v[190:193], v[24:27]
	v_mfma_f32_16x16x32_bf16 v[16:19], v[166:169], v[190:193], v[16:19]
	v_mfma_f32_16x16x32_bf16 v[8:11], v[158:161], v[198:201], v[8:11]
	v_mfma_f32_16x16x32_bf16 v[0:3], v[166:169], v[198:201], v[0:3]
	v_mfma_f32_16x16x32_bf16 v[56:59], v[162:165], v[178:181], v[56:59]
	v_mfma_f32_16x16x32_bf16 v[48:51], v[170:173], v[178:181], v[48:51]
	v_mfma_f32_16x16x32_bf16 v[40:43], v[162:165], v[186:189], v[40:43]
	v_mfma_f32_16x16x32_bf16 v[32:35], v[170:173], v[186:189], v[32:35]
	v_mfma_f32_16x16x32_bf16 v[24:27], v[162:165], v[194:197], v[24:27]
	v_mfma_f32_16x16x32_bf16 v[16:19], v[170:173], v[194:197], v[16:19]
	v_mfma_f32_16x16x32_bf16 v[8:11], v[162:165], v[202:205], v[8:11]
	v_mfma_f32_16x16x32_bf16 v[0:3], v[170:173], v[202:205], v[0:3]
	s_barrier
	s_add_u32 s64, s36, 0x40000
	s_addc_u32 s65, s37, 0
	s_mov_b32 m0, s55
	v_lshl_add_u64 v[158:159], s[64:65], 0, v[134:135]
	global_load_lds_dwordx4 v[158:159], off
	s_mov_b32 m0, s56
	v_lshl_add_u64 v[158:159], s[64:65], 0, v[130:131]
	global_load_lds_dwordx4 v[158:159], off
	s_waitcnt vmcnt(6)
	s_barrier
	v_mfma_f32_16x16x32_bf16 v[68:71], v[206:209], v[174:177], v[68:71]
	v_mfma_f32_16x16x32_bf16 v[52:55], v[214:217], v[174:177], v[52:55]
	v_mfma_f32_16x16x32_bf16 v[44:47], v[206:209], v[182:185], v[44:47]
	v_mfma_f32_16x16x32_bf16 v[36:39], v[214:217], v[182:185], v[36:39]
	v_mfma_f32_16x16x32_bf16 v[28:31], v[206:209], v[190:193], v[28:31]
	v_mfma_f32_16x16x32_bf16 v[20:23], v[214:217], v[190:193], v[20:23]
	v_mfma_f32_16x16x32_bf16 v[12:15], v[206:209], v[198:201], v[12:15]
	v_mfma_f32_16x16x32_bf16 v[4:7], v[214:217], v[198:201], v[4:7]
	v_mfma_f32_16x16x32_bf16 v[68:71], v[210:213], v[178:181], v[68:71]
	v_mfma_f32_16x16x32_bf16 v[52:55], v[222:225], v[178:181], v[52:55]
	v_mfma_f32_16x16x32_bf16 v[44:47], v[210:213], v[186:189], v[44:47]
	v_mfma_f32_16x16x32_bf16 v[36:39], v[222:225], v[186:189], v[36:39]
	v_mfma_f32_16x16x32_bf16 v[28:31], v[210:213], v[194:197], v[28:31]
	v_mfma_f32_16x16x32_bf16 v[20:23], v[222:225], v[194:197], v[20:23]
	v_mfma_f32_16x16x32_bf16 v[12:15], v[210:213], v[202:205], v[12:15]
	v_mfma_f32_16x16x32_bf16 v[4:7], v[222:225], v[202:205], v[4:7]
	s_barrier
	ds_read_b128 v[158:161], v155
	ds_read_b128 v[162:165], v155 offset:1024
	ds_read_b128 v[166:169], v155 offset:2048
	ds_read_b128 v[170:173], v155 offset:3072
	s_add_u32 s62, s62, 0x40000
	s_addc_u32 s63, s63, 0
	s_mov_b32 m0, s42
	v_lshl_add_u64 v[206:207], s[62:63], 0, v[136:137]
	ds_read_b128 v[174:177], v153 offset:32768
	ds_read_b128 v[178:181], v153 offset:33792
	ds_read_b128 v[182:185], v153 offset:34816
	ds_read_b128 v[186:189], v153 offset:35840
	ds_read_b128 v[190:193], v153 offset:36864
	ds_read_b128 v[194:197], v153 offset:37888
	ds_read_b128 v[198:201], v153 offset:38912
	ds_read_b128 v[202:205], v153 offset:39936
	global_load_lds_dwordx4 v[206:207], off
	s_mov_b32 m0, s43
	v_lshl_add_u64 v[206:207], s[62:63], 0, v[132:133]
	global_load_lds_dwordx4 v[206:207], off
	s_waitcnt lgkmcnt(8)
	s_barrier
	s_waitcnt lgkmcnt(0)
	v_mfma_f32_16x16x32_bf16 v[120:123], v[158:161], v[174:177], v[120:123]
	v_mfma_f32_16x16x32_bf16 v[112:115], v[166:169], v[174:177], v[112:115]
	v_mfma_f32_16x16x32_bf16 v[104:107], v[158:161], v[182:185], v[104:107]
	v_mfma_f32_16x16x32_bf16 v[96:99], v[166:169], v[182:185], v[96:99]
	v_mfma_f32_16x16x32_bf16 v[88:91], v[158:161], v[190:193], v[88:91]
	v_mfma_f32_16x16x32_bf16 v[80:83], v[166:169], v[190:193], v[80:83]
	v_mfma_f32_16x16x32_bf16 v[72:75], v[158:161], v[198:201], v[72:75]
	v_mfma_f32_16x16x32_bf16 v[60:63], v[166:169], v[198:201], v[60:63]
	v_mfma_f32_16x16x32_bf16 v[120:123], v[162:165], v[178:181], v[120:123]
	v_mfma_f32_16x16x32_bf16 v[112:115], v[170:173], v[178:181], v[112:115]
	v_mfma_f32_16x16x32_bf16 v[104:107], v[162:165], v[186:189], v[104:107]
	v_mfma_f32_16x16x32_bf16 v[96:99], v[170:173], v[186:189], v[96:99]
	v_mfma_f32_16x16x32_bf16 v[88:91], v[162:165], v[194:197], v[88:91]
	v_mfma_f32_16x16x32_bf16 v[80:83], v[170:173], v[194:197], v[80:83]
	v_mfma_f32_16x16x32_bf16 v[72:75], v[162:165], v[202:205], v[72:75]
	v_mfma_f32_16x16x32_bf16 v[60:63], v[170:173], v[202:205], v[60:63]
	s_barrier
	s_mov_b32 m0, s57
	v_lshl_add_u64 v[218:219], v[218:219], 0, s[6:7]
	ds_read_b128 v[206:209], v156
	ds_read_b128 v[210:213], v156 offset:1024
	ds_read_b128 v[214:217], v156 offset:2048
	ds_read_b128 v[222:225], v156 offset:3072
	global_load_lds_dwordx4 v[218:219], off
	s_mov_b32 m0, s58
	v_lshl_add_u64 v[218:219], v[226:227], 0, s[6:7]
	global_load_lds_dwordx4 v[218:219], off
	s_barrier
	s_waitcnt lgkmcnt(0)
	v_mfma_f32_16x16x32_bf16 v[124:127], v[206:209], v[174:177], v[124:127]
	v_mfma_f32_16x16x32_bf16 v[116:119], v[214:217], v[174:177], v[116:119]
	v_mfma_f32_16x16x32_bf16 v[108:111], v[206:209], v[182:185], v[108:111]
	v_mfma_f32_16x16x32_bf16 v[100:103], v[214:217], v[182:185], v[100:103]
	v_mfma_f32_16x16x32_bf16 v[92:95], v[206:209], v[190:193], v[92:95]
	v_mfma_f32_16x16x32_bf16 v[84:87], v[214:217], v[190:193], v[84:87]
	v_mfma_f32_16x16x32_bf16 v[76:79], v[206:209], v[198:201], v[76:79]
	v_mfma_f32_16x16x32_bf16 v[64:67], v[214:217], v[198:201], v[64:67]
	v_mfma_f32_16x16x32_bf16 v[124:127], v[210:213], v[178:181], v[124:127]
	v_mfma_f32_16x16x32_bf16 v[116:119], v[222:225], v[178:181], v[116:119]
	v_mfma_f32_16x16x32_bf16 v[108:111], v[210:213], v[186:189], v[108:111]
	v_mfma_f32_16x16x32_bf16 v[100:103], v[222:225], v[186:189], v[100:103]
	v_mfma_f32_16x16x32_bf16 v[92:95], v[210:213], v[194:197], v[92:95]
	v_mfma_f32_16x16x32_bf16 v[84:87], v[222:225], v[194:197], v[84:87]
	v_mfma_f32_16x16x32_bf16 v[76:79], v[210:213], v[202:205], v[76:79]
	v_mfma_f32_16x16x32_bf16 v[64:67], v[222:225], v[202:205], v[64:67]
	s_mov_b32 m0, s44
	v_lshl_add_u64 v[218:219], v[228:229], 0, s[6:7]
	s_barrier
	ds_read_b128 v[174:177], v153 offset:49152
	ds_read_b128 v[178:181], v153 offset:50176
	ds_read_b128 v[182:185], v153 offset:51200
	ds_read_b128 v[186:189], v153 offset:52224
	ds_read_b128 v[190:193], v153 offset:53248
	ds_read_b128 v[194:197], v153 offset:54272
	ds_read_b128 v[198:201], v153 offset:55296
	ds_read_b128 v[202:205], v153 offset:56320
	global_load_lds_dwordx4 v[218:219], off
	s_mov_b32 m0, s45
	v_lshl_add_u64 v[218:219], v[230:231], 0, s[6:7]
	global_load_lds_dwordx4 v[218:219], off
	s_barrier
; __device__ __forceinline__ unsigned pk2(float lo, float hi) { unsigned r; asm volatile("v_cvt_pk_bf16_f32 %0, %1, %2" : "=v"(r) : "v"(lo), "v"(hi)); return r; }
; __device__ __forceinline__ unsigned pk2(float lo, float hi) { return f2bf(lo) | (f2bf(hi) << 16); }
;     ...
;         G_PAIR(0, 1);
; #pragma unroll 1
;         for (int t = 2; t < nt; t += 2) G_PAIR(t, 0);
;     __device__ __forceinline__ void epi(const f32x4 (&acc)[2][2][4][2], const Unit& u, int wr, int wc, int fr, int fq) const {
;     ...
;             for (int m = 0; m < 4; ++m) {
;                 const int row = row0 + ai * 128 + m * 16; const float rs = rs_lds[((u.pm >> 3) & 1) * 256 + (row & 255)];
;                 const float rs2 = rs * -1.4426950408889634f, rsq = rs * rs;
;                 f32x2 v[4];
; #pragma unroll
;                 for (int n = 0; n < 2; ++n)
; #pragma unroll
;                     for (int jp = 0; jp < 2; ++jp) {
;                         const f32x2 gg = (f32x2){acc[ai][0][m][n][2 * jp], acc[ai][0][m][n][2 * jp + 1]}, uu = (f32x2){acc[ai][1][m][n][2 * jp], acc[ai][1][m][n][2 * jp + 1]};
;                         const f32x2 t = gg * rs2; f32x2 e; e.x = __builtin_amdgcn_exp2f(t.x); e.y = __builtin_amdgcn_exp2f(t.y);
;                         const f32x2 d = e + 1.0f; f32x2 r; r.x = __builtin_amdgcn_rcpf(d.x); r.y = __builtin_amdgcn_rcpf(d.y);
;                         v[n * 2 + jp] = (gg * uu) * (r * rsq);
;                     }
;                 u32x4 w; w.x = pk2(v[0].x, v[0].y); w.y = pk2(v[1].x, v[1].y); w.z = pk2(v[2].x, v[2].y); w.w = pk2(v[3].x, v[3].y);
;                 *(u32x4*)(H + (size_t)row * FF + col0) = w;
	s_waitcnt lgkmcnt(0)
	v_mfma_f32_16x16x32_bf16 v[56:59], v[158:161], v[174:177], v[56:59]
	v_mfma_f32_16x16x32_bf16 v[48:51], v[166:169], v[174:177], v[48:51]
	v_mfma_f32_16x16x32_bf16 v[40:43], v[158:161], v[182:185], v[40:43]
	v_mfma_f32_16x16x32_bf16 v[32:35], v[166:169], v[182:185], v[32:35]
	v_mfma_f32_16x16x32_bf16 v[24:27], v[158:161], v[190:193], v[24:27]
	v_mfma_f32_16x16x32_bf16 v[16:19], v[166:169], v[190:193], v[16:19]
	v_mfma_f32_16x16x32_bf16 v[8:11], v[158:161], v[198:201], v[8:11]
	v_mfma_f32_16x16x32_bf16 v[0:3], v[166:169], v[198:201], v[0:3]
	v_mfma_f32_16x16x32_bf16 v[56:59], v[162:165], v[178:181], v[56:59]
	v_mfma_f32_16x16x32_bf16 v[48:51], v[170:173], v[178:181], v[48:51]
	v_mfma_f32_16x16x32_bf16 v[40:43], v[162:165], v[186:189], v[40:43]
	v_mfma_f32_16x16x32_bf16 v[32:35], v[170:173], v[186:189], v[32:35]
	v_mfma_f32_16x16x32_bf16 v[24:27], v[162:165], v[194:197], v[24:27]
	v_mfma_f32_16x16x32_bf16 v[16:19], v[170:173], v[194:197], v[16:19]
	v_mfma_f32_16x16x32_bf16 v[8:11], v[162:165], v[202:205], v[8:11]
	v_mfma_f32_16x16x32_bf16 v[0:3], v[170:173], v[202:205], v[0:3]
	s_barrier
	s_add_u32 s36, s36, 0x40080
	s_addc_u32 s37, s37, 0
	s_mov_b32 m0, s59
	v_lshl_add_u64 v[158:159], s[36:37], 0, v[134:135]
	global_load_lds_dwordx4 v[158:159], off
	s_mov_b32 m0, s17
	v_lshl_add_u64 v[158:159], s[36:37], 0, v[130:131]
	global_load_lds_dwordx4 v[158:159], off
	s_waitcnt vmcnt(6)
	s_barrier
	v_mfma_f32_16x16x32_bf16 v[68:71], v[206:209], v[174:177], v[68:71]
	v_mfma_f32_16x16x32_bf16 v[52:55], v[214:217], v[174:177], v[52:55]
	v_mfma_f32_16x16x32_bf16 v[44:47], v[206:209], v[182:185], v[44:47]
	v_mfma_f32_16x16x32_bf16 v[36:39], v[214:217], v[182:185], v[36:39]
	v_mfma_f32_16x16x32_bf16 v[28:31], v[206:209], v[190:193], v[28:31]
	v_mfma_f32_16x16x32_bf16 v[20:23], v[214:217], v[190:193], v[20:23]
	v_mfma_f32_16x16x32_bf16 v[12:15], v[206:209], v[198:201], v[12:15]
	v_mfma_f32_16x16x32_bf16 v[4:7], v[214:217], v[198:201], v[4:7]
	v_mfma_f32_16x16x32_bf16 v[68:71], v[210:213], v[178:181], v[68:71]
	v_mfma_f32_16x16x32_bf16 v[52:55], v[222:225], v[178:181], v[52:55]
	v_mfma_f32_16x16x32_bf16 v[44:47], v[210:213], v[186:189], v[44:47]
	v_mfma_f32_16x16x32_bf16 v[36:39], v[222:225], v[186:189], v[36:39]
	v_mfma_f32_16x16x32_bf16 v[28:31], v[210:213], v[194:197], v[28:31]
	v_mfma_f32_16x16x32_bf16 v[20:23], v[222:225], v[194:197], v[20:23]
	v_mfma_f32_16x16x32_bf16 v[12:15], v[210:213], v[202:205], v[12:15]
	v_mfma_f32_16x16x32_bf16 v[4:7], v[222:225], v[202:205], v[4:7]
	s_add_i32 s19, s19, 2
	s_add_u32 s34, s34, 0x100
	s_addc_u32 s35, s35, 0
	s_cmp_gt_u32 s19, 13
	s_cbranch_scc0 .Lrot_232
	s_barrier
	s_lshl_b32 s17, s24, 7
	s_and_b32 s17, s17, 0x400
	s_add_i32 s17, s17, 0x20000
	v_lshl_add_u32 v142, v151, 2, s17
	ds_read_b32 v143, v142
	s_waitcnt lgkmcnt(0)
	v_mul_f32_e32 v144, 0xbfb8aa3b, v143
	v_mul_f32_e32 v164, v143, v143
	ds_read_b32 v143, v142 offset:64
	v_pk_mul_f32 v[160:161], v[120:121], v[144:145] op_sel_hi:[1,0]
	v_pk_mul_f32 v[162:163], v[122:123], v[144:145] op_sel_hi:[1,0]
	v_exp_f32_e32 v160, v160
	v_exp_f32_e32 v161, v161
	v_exp_f32_e32 v162, v162
	v_exp_f32_e32 v163, v163
	v_pk_mul_f32 v[120:121], v[120:121], v[124:125]
	v_pk_add_f32 v[160:161], v[160:161], 1.0 op_sel_hi:[1,0]
	v_pk_mul_f32 v[122:123], v[122:123], v[126:127]
	v_pk_add_f32 v[162:163], v[162:163], 1.0 op_sel_hi:[1,0]
	v_rcp_f32_e32 v160, v160
	v_rcp_f32_e32 v161, v161
	v_rcp_f32_e32 v162, v162
	v_rcp_f32_e32 v163, v163
	v_pk_mul_f32 v[160:161], v[164:165], v[160:161] op_sel_hi:[0,1]
	v_pk_mul_f32 v[120:121], v[120:121], v[160:161]
	v_pk_mul_f32 v[162:163], v[164:165], v[162:163] op_sel_hi:[0,1]
	v_pk_mul_f32 v[122:123], v[122:123], v[162:163]
	v_pk_mul_f32 v[160:161], v[112:113], v[144:145] op_sel_hi:[1,0]
	v_pk_mul_f32 v[162:163], v[114:115], v[144:145] op_sel_hi:[1,0]
	v_exp_f32_e32 v160, v160
	v_exp_f32_e32 v161, v161
	v_exp_f32_e32 v162, v162
	v_exp_f32_e32 v163, v163
	v_pk_mul_f32 v[112:113], v[112:113], v[116:117]
	v_pk_add_f32 v[160:161], v[160:161], 1.0 op_sel_hi:[1,0]
	v_pk_mul_f32 v[114:115], v[114:115], v[118:119]
	v_pk_add_f32 v[162:163], v[162:163], 1.0 op_sel_hi:[1,0]
	v_rcp_f32_e32 v160, v160
	v_rcp_f32_e32 v161, v161
	v_rcp_f32_e32 v162, v162
	v_rcp_f32_e32 v163, v163
	v_pk_mul_f32 v[160:161], v[164:165], v[160:161] op_sel_hi:[0,1]
	v_pk_mul_f32 v[112:113], v[112:113], v[160:161]
	v_pk_mul_f32 v[162:163], v[164:165], v[162:163] op_sel_hi:[0,1]
	v_pk_mul_f32 v[114:115], v[114:115], v[162:163]
	v_cvt_pk_bf16_f32 v124, v120, v121
	v_cvt_pk_bf16_f32 v125, v122, v123
	v_cvt_pk_bf16_f32 v126, v112, v113
	v_cvt_pk_bf16_f32 v127, v114, v115
	v_lshl_add_u32 v112, s24, 8, v129
	v_lshl_or_b32 v114, s60, 7, v150
	v_mov_b64_e32 v[116:117], s[2:3]
	v_ashrrev_i32_e32 v115, 31, v114
	v_mad_i64_i32 v[118:119], s[26:27], v112, s51, v[116:117]
	v_lshlrev_b64 v[114:115], 1, v[114:115]
	v_mov_b32_e32 v112, 0xb0000
	v_mov_b32_e32 v113, 0
	v_lshl_add_u64 v[118:119], v[118:119], 0, v[114:115]
	v_mov_b32_e32 v120, 0x16000
	v_mov_b32_e32 v121, 0
	v_lshl_add_u64 v[122:123], v[118:119], 0, v[112:113]
	s_mov_b32 s60, s16
	s_mov_b32 s24, s18
	global_store_dwordx4 v[118:119], v[124:127], off
	s_waitcnt lgkmcnt(0)
; __device__ __forceinline__ unsigned pk2(float lo, float hi) { unsigned r; asm volatile("v_cvt_pk_bf16_f32 %0, %1, %2" : "=v"(r) : "v"(lo), "v"(hi)); return r; }
; __device__ __forceinline__ unsigned pk2(float lo, float hi) { return f2bf(lo) | (f2bf(hi) << 16); }
;     __device__ __forceinline__ void epi(const f32x4 (&acc)[2][2][4][2], const Unit& u, int wr, int wc, int fr, int fq) const {
;     ...
;                 const int row = row0 + ai * 128 + m * 16; const float rs = rs_lds[((u.pm >> 3) & 1) * 256 + (row & 255)];
;                 const float rs2 = rs * -1.4426950408889634f, rsq = rs * rs;
;                 f32x2 v[4];
; #pragma unroll
;                 for (int n = 0; n < 2; ++n)
; #pragma unroll
;                     for (int jp = 0; jp < 2; ++jp) {
;                         const f32x2 gg = (f32x2){acc[ai][0][m][n][2 * jp], acc[ai][0][m][n][2 * jp + 1]}, uu = (f32x2){acc[ai][1][m][n][2 * jp], acc[ai][1][m][n][2 * jp + 1]};
;                         const f32x2 t = gg * rs2; f32x2 e; e.x = __builtin_amdgcn_exp2f(t.x); e.y = __builtin_amdgcn_exp2f(t.y);
;                         const f32x2 d = e + 1.0f; f32x2 r; r.x = __builtin_amdgcn_rcpf(d.x); r.y = __builtin_amdgcn_rcpf(d.y);
;                         v[n * 2 + jp] = (gg * uu) * (r * rsq);
;                     }
;                 u32x4 w; w.x = pk2(v[0].x, v[0].y); w.y = pk2(v[1].x, v[1].y); w.z = pk2(v[2].x, v[2].y); w.w = pk2(v[3].x, v[3].y);
;                 *(u32x4*)(H + (size_t)row * FF + col0) = w;
	v_mul_f32_e32 v144, 0xbfb8aa3b, v143
	v_mul_f32_e32 v164, v143, v143
	ds_read_b32 v143, v142 offset:128
	v_pk_mul_f32 v[160:161], v[104:105], v[144:145] op_sel_hi:[1,0]
	v_pk_mul_f32 v[162:163], v[106:107], v[144:145] op_sel_hi:[1,0]
	v_exp_f32_e32 v160, v160
	v_exp_f32_e32 v161, v161
	v_exp_f32_e32 v162, v162
	v_exp_f32_e32 v163, v163
	v_pk_mul_f32 v[104:105], v[104:105], v[108:109]
	v_pk_add_f32 v[160:161], v[160:161], 1.0 op_sel_hi:[1,0]
	v_pk_mul_f32 v[106:107], v[106:107], v[110:111]
	v_pk_add_f32 v[162:163], v[162:163], 1.0 op_sel_hi:[1,0]
	v_rcp_f32_e32 v160, v160
	v_rcp_f32_e32 v161, v161
	v_rcp_f32_e32 v162, v162
	v_rcp_f32_e32 v163, v163
	v_pk_mul_f32 v[160:161], v[164:165], v[160:161] op_sel_hi:[0,1]
	v_pk_mul_f32 v[104:105], v[104:105], v[160:161]
	v_pk_mul_f32 v[162:163], v[164:165], v[162:163] op_sel_hi:[0,1]
	v_pk_mul_f32 v[106:107], v[106:107], v[162:163]
	v_pk_mul_f32 v[160:161], v[96:97], v[144:145] op_sel_hi:[1,0]
	v_pk_mul_f32 v[162:163], v[98:99], v[144:145] op_sel_hi:[1,0]
	v_exp_f32_e32 v160, v160
	v_exp_f32_e32 v161, v161
	v_exp_f32_e32 v162, v162
	v_exp_f32_e32 v163, v163
	v_pk_mul_f32 v[96:97], v[96:97], v[100:101]
	v_pk_add_f32 v[160:161], v[160:161], 1.0 op_sel_hi:[1,0]
	v_pk_mul_f32 v[98:99], v[98:99], v[102:103]
	v_pk_add_f32 v[162:163], v[162:163], 1.0 op_sel_hi:[1,0]
	v_rcp_f32_e32 v160, v160
	v_rcp_f32_e32 v161, v161
	v_rcp_f32_e32 v162, v162
	v_rcp_f32_e32 v163, v163
	v_pk_mul_f32 v[160:161], v[164:165], v[160:161] op_sel_hi:[0,1]
	v_pk_mul_f32 v[96:97], v[96:97], v[160:161]
	v_pk_mul_f32 v[162:163], v[164:165], v[162:163] op_sel_hi:[0,1]
	v_pk_mul_f32 v[98:99], v[98:99], v[162:163]
	v_cvt_pk_bf16_f32 v108, v104, v105
	v_cvt_pk_bf16_f32 v109, v106, v107
	v_cvt_pk_bf16_f32 v110, v96, v97
	v_cvt_pk_bf16_f32 v111, v98, v99
	v_lshl_add_u64 v[118:119], v[118:119], 0, v[120:121]
	global_store_dwordx4 v[118:119], v[108:111], off
	s_waitcnt lgkmcnt(0)
	v_mul_f32_e32 v144, 0xbfb8aa3b, v143
	v_mul_f32_e32 v164, v143, v143
	ds_read_b32 v143, v142 offset:192
	v_pk_mul_f32 v[160:161], v[88:89], v[144:145] op_sel_hi:[1,0]
	v_pk_mul_f32 v[162:163], v[90:91], v[144:145] op_sel_hi:[1,0]
	v_exp_f32_e32 v160, v160
	v_exp_f32_e32 v161, v161
	v_exp_f32_e32 v162, v162
	v_exp_f32_e32 v163, v163
	v_pk_mul_f32 v[88:89], v[88:89], v[92:93]
	v_pk_add_f32 v[160:161], v[160:161], 1.0 op_sel_hi:[1,0]
	v_pk_mul_f32 v[90:91], v[90:91], v[94:95]
	v_pk_add_f32 v[162:163], v[162:163], 1.0 op_sel_hi:[1,0]
	v_rcp_f32_e32 v160, v160
	v_rcp_f32_e32 v161, v161
	v_rcp_f32_e32 v162, v162
	v_rcp_f32_e32 v163, v163
	v_pk_mul_f32 v[160:161], v[164:165], v[160:161] op_sel_hi:[0,1]
	v_pk_mul_f32 v[88:89], v[88:89], v[160:161]
	v_pk_mul_f32 v[162:163], v[164:165], v[162:163] op_sel_hi:[0,1]
	v_pk_mul_f32 v[90:91], v[90:91], v[162:163]
	v_pk_mul_f32 v[160:161], v[80:81], v[144:145] op_sel_hi:[1,0]
	v_pk_mul_f32 v[162:163], v[82:83], v[144:145] op_sel_hi:[1,0]
	v_exp_f32_e32 v160, v160
	v_exp_f32_e32 v161, v161
	v_exp_f32_e32 v162, v162
	v_exp_f32_e32 v163, v163
	v_pk_mul_f32 v[80:81], v[80:81], v[84:85]
	v_pk_add_f32 v[160:161], v[160:161], 1.0 op_sel_hi:[1,0]
	v_pk_mul_f32 v[82:83], v[82:83], v[86:87]
	v_pk_add_f32 v[162:163], v[162:163], 1.0 op_sel_hi:[1,0]
	v_rcp_f32_e32 v160, v160
	v_rcp_f32_e32 v161, v161
	v_rcp_f32_e32 v162, v162
	v_rcp_f32_e32 v163, v163
	v_pk_mul_f32 v[160:161], v[164:165], v[160:161] op_sel_hi:[0,1]
	v_pk_mul_f32 v[80:81], v[80:81], v[160:161]
	v_pk_mul_f32 v[162:163], v[164:165], v[162:163] op_sel_hi:[0,1]
	v_pk_mul_f32 v[82:83], v[82:83], v[162:163]
	v_cvt_pk_bf16_f32 v92, v88, v89
	v_cvt_pk_bf16_f32 v93, v90, v91
	v_cvt_pk_bf16_f32 v94, v80, v81
	v_cvt_pk_bf16_f32 v95, v82, v83
	v_lshl_add_u64 v[118:119], v[118:119], 0, v[120:121]
	global_store_dwordx4 v[118:119], v[92:95], off
	s_waitcnt lgkmcnt(0)
	v_mul_f32_e32 v144, 0xbfb8aa3b, v143
	v_mul_f32_e32 v164, v143, v143
	ds_read_b32 v143, v142 offset:512
	v_pk_mul_f32 v[160:161], v[72:73], v[144:145] op_sel_hi:[1,0]
	v_pk_mul_f32 v[162:163], v[74:75], v[144:145] op_sel_hi:[1,0]
	v_exp_f32_e32 v160, v160
	v_exp_f32_e32 v161, v161
	v_exp_f32_e32 v162, v162
	v_exp_f32_e32 v163, v163
	v_pk_mul_f32 v[72:73], v[72:73], v[76:77]
	v_pk_add_f32 v[160:161], v[160:161], 1.0 op_sel_hi:[1,0]
	v_pk_mul_f32 v[74:75], v[74:75], v[78:79]
	v_pk_add_f32 v[162:163], v[162:163], 1.0 op_sel_hi:[1,0]
	v_rcp_f32_e32 v160, v160
	v_rcp_f32_e32 v161, v161
	v_rcp_f32_e32 v162, v162
	v_rcp_f32_e32 v163, v163
	v_pk_mul_f32 v[160:161], v[164:165], v[160:161] op_sel_hi:[0,1]
	v_pk_mul_f32 v[72:73], v[72:73], v[160:161]
	v_pk_mul_f32 v[162:163], v[164:165], v[162:163] op_sel_hi:[0,1]
	v_pk_mul_f32 v[74:75], v[74:75], v[162:163]
	v_pk_mul_f32 v[160:161], v[60:61], v[144:145] op_sel_hi:[1,0]
	v_pk_mul_f32 v[162:163], v[62:63], v[144:145] op_sel_hi:[1,0]
	v_exp_f32_e32 v160, v160
	v_exp_f32_e32 v161, v161
	v_exp_f32_e32 v162, v162
	v_exp_f32_e32 v163, v163
	v_pk_mul_f32 v[60:61], v[60:61], v[64:65]
	v_pk_add_f32 v[160:161], v[160:161], 1.0 op_sel_hi:[1,0]
	v_pk_mul_f32 v[62:63], v[62:63], v[66:67]
	v_pk_add_f32 v[162:163], v[162:163], 1.0 op_sel_hi:[1,0]
	v_rcp_f32_e32 v160, v160
	v_rcp_f32_e32 v161, v161
	v_rcp_f32_e32 v162, v162
	v_rcp_f32_e32 v163, v163
	v_pk_mul_f32 v[160:161], v[164:165], v[160:161] op_sel_hi:[0,1]
	v_pk_mul_f32 v[60:61], v[60:61], v[160:161]
	v_pk_mul_f32 v[162:163], v[164:165], v[162:163] op_sel_hi:[0,1]
	v_pk_mul_f32 v[62:63], v[62:63], v[162:163]
	v_cvt_pk_bf16_f32 v76, v72, v73
	v_cvt_pk_bf16_f32 v77, v74, v75
	v_cvt_pk_bf16_f32 v78, v60, v61
	v_cvt_pk_bf16_f32 v79, v62, v63
	v_lshl_add_u64 v[118:119], v[118:119], 0, v[120:121]
	global_store_dwordx4 v[118:119], v[76:79], off
	s_waitcnt lgkmcnt(0)
; __device__ __forceinline__ unsigned pk2(float lo, float hi) { unsigned r; asm volatile("v_cvt_pk_bf16_f32 %0, %1, %2" : "=v"(r) : "v"(lo), "v"(hi)); return r; }
; __device__ __forceinline__ unsigned pk2(float lo, float hi) { return f2bf(lo) | (f2bf(hi) << 16); }
;     __device__ __forceinline__ void epi(const f32x4 (&acc)[2][2][4][2], const Unit& u, int wr, int wc, int fr, int fq) const {
;     ...
;                 const int row = row0 + ai * 128 + m * 16; const float rs = rs_lds[((u.pm >> 3) & 1) * 256 + (row & 255)];
;                 const float rs2 = rs * -1.4426950408889634f, rsq = rs * rs;
;                 f32x2 v[4];
; #pragma unroll
;                 for (int n = 0; n < 2; ++n)
; #pragma unroll
;                     for (int jp = 0; jp < 2; ++jp) {
;                         const f32x2 gg = (f32x2){acc[ai][0][m][n][2 * jp], acc[ai][0][m][n][2 * jp + 1]}, uu = (f32x2){acc[ai][1][m][n][2 * jp], acc[ai][1][m][n][2 * jp + 1]};
;                         const f32x2 t = gg * rs2; f32x2 e; e.x = __builtin_amdgcn_exp2f(t.x); e.y = __builtin_amdgcn_exp2f(t.y);
;                         const f32x2 d = e + 1.0f; f32x2 r; r.x = __builtin_amdgcn_rcpf(d.x); r.y = __builtin_amdgcn_rcpf(d.y);
;                         v[n * 2 + jp] = (gg * uu) * (r * rsq);
;                     }
;                 u32x4 w; w.x = pk2(v[0].x, v[0].y); w.y = pk2(v[1].x, v[1].y); w.z = pk2(v[2].x, v[2].y); w.w = pk2(v[3].x, v[3].y);
;                 *(u32x4*)(H + (size_t)row * FF + col0) = w;
	v_mul_f32_e32 v144, 0xbfb8aa3b, v143
	v_mul_f32_e32 v164, v143, v143
	ds_read_b32 v143, v142 offset:576
	v_pk_mul_f32 v[160:161], v[56:57], v[144:145] op_sel_hi:[1,0]
	v_pk_mul_f32 v[162:163], v[58:59], v[144:145] op_sel_hi:[1,0]
	v_exp_f32_e32 v160, v160
	v_exp_f32_e32 v161, v161
	v_exp_f32_e32 v162, v162
	v_exp_f32_e32 v163, v163
	v_pk_mul_f32 v[56:57], v[56:57], v[68:69]
	v_pk_add_f32 v[160:161], v[160:161], 1.0 op_sel_hi:[1,0]
	v_pk_mul_f32 v[58:59], v[58:59], v[70:71]
	v_pk_add_f32 v[162:163], v[162:163], 1.0 op_sel_hi:[1,0]
	v_rcp_f32_e32 v160, v160
	v_rcp_f32_e32 v161, v161
	v_rcp_f32_e32 v162, v162
	v_rcp_f32_e32 v163, v163
	v_pk_mul_f32 v[160:161], v[164:165], v[160:161] op_sel_hi:[0,1]
	v_pk_mul_f32 v[56:57], v[56:57], v[160:161]
	v_pk_mul_f32 v[162:163], v[164:165], v[162:163] op_sel_hi:[0,1]
	v_pk_mul_f32 v[58:59], v[58:59], v[162:163]
	v_pk_mul_f32 v[160:161], v[48:49], v[144:145] op_sel_hi:[1,0]
	v_pk_mul_f32 v[162:163], v[50:51], v[144:145] op_sel_hi:[1,0]
	v_exp_f32_e32 v160, v160
	v_exp_f32_e32 v161, v161
	v_exp_f32_e32 v162, v162
	v_exp_f32_e32 v163, v163
	v_pk_mul_f32 v[48:49], v[48:49], v[52:53]
	v_pk_add_f32 v[160:161], v[160:161], 1.0 op_sel_hi:[1,0]
	v_pk_mul_f32 v[50:51], v[50:51], v[54:55]
	v_pk_add_f32 v[162:163], v[162:163], 1.0 op_sel_hi:[1,0]
	v_rcp_f32_e32 v160, v160
	v_rcp_f32_e32 v161, v161
	v_rcp_f32_e32 v162, v162
	v_rcp_f32_e32 v163, v163
	v_pk_mul_f32 v[160:161], v[164:165], v[160:161] op_sel_hi:[0,1]
	v_pk_mul_f32 v[48:49], v[48:49], v[160:161]
	v_pk_mul_f32 v[162:163], v[164:165], v[162:163] op_sel_hi:[0,1]
	v_pk_mul_f32 v[50:51], v[50:51], v[162:163]
	v_cvt_pk_bf16_f32 v68, v56, v57
	v_cvt_pk_bf16_f32 v69, v58, v59
	v_cvt_pk_bf16_f32 v70, v48, v49
	v_cvt_pk_bf16_f32 v71, v50, v51
	v_mov_b64_e32 v[118:119], v[122:123]
	global_store_dwordx4 v[118:119], v[68:71], off
	s_waitcnt lgkmcnt(0)
	v_mul_f32_e32 v144, 0xbfb8aa3b, v143
	v_mul_f32_e32 v164, v143, v143
	ds_read_b32 v143, v142 offset:640
	v_pk_mul_f32 v[160:161], v[40:41], v[144:145] op_sel_hi:[1,0]
	v_pk_mul_f32 v[162:163], v[42:43], v[144:145] op_sel_hi:[1,0]
	v_exp_f32_e32 v160, v160
	v_exp_f32_e32 v161, v161
	v_exp_f32_e32 v162, v162
	v_exp_f32_e32 v163, v163
	v_pk_mul_f32 v[40:41], v[40:41], v[44:45]
	v_pk_add_f32 v[160:161], v[160:161], 1.0 op_sel_hi:[1,0]
	v_pk_mul_f32 v[42:43], v[42:43], v[46:47]
	v_pk_add_f32 v[162:163], v[162:163], 1.0 op_sel_hi:[1,0]
	v_rcp_f32_e32 v160, v160
	v_rcp_f32_e32 v161, v161
	v_rcp_f32_e32 v162, v162
	v_rcp_f32_e32 v163, v163
	v_pk_mul_f32 v[160:161], v[164:165], v[160:161] op_sel_hi:[0,1]
	v_pk_mul_f32 v[40:41], v[40:41], v[160:161]
	v_pk_mul_f32 v[162:163], v[164:165], v[162:163] op_sel_hi:[0,1]
	v_pk_mul_f32 v[42:43], v[42:43], v[162:163]
	v_pk_mul_f32 v[160:161], v[32:33], v[144:145] op_sel_hi:[1,0]
	v_pk_mul_f32 v[162:163], v[34:35], v[144:145] op_sel_hi:[1,0]
	v_exp_f32_e32 v160, v160
	v_exp_f32_e32 v161, v161
	v_exp_f32_e32 v162, v162
	v_exp_f32_e32 v163, v163
	v_pk_mul_f32 v[32:33], v[32:33], v[36:37]
	v_pk_add_f32 v[160:161], v[160:161], 1.0 op_sel_hi:[1,0]
	v_pk_mul_f32 v[34:35], v[34:35], v[38:39]
	v_pk_add_f32 v[162:163], v[162:163], 1.0 op_sel_hi:[1,0]
	v_rcp_f32_e32 v160, v160
	v_rcp_f32_e32 v161, v161
	v_rcp_f32_e32 v162, v162
	v_rcp_f32_e32 v163, v163
	v_pk_mul_f32 v[160:161], v[164:165], v[160:161] op_sel_hi:[0,1]
	v_pk_mul_f32 v[32:33], v[32:33], v[160:161]
	v_pk_mul_f32 v[162:163], v[164:165], v[162:163] op_sel_hi:[0,1]
	v_pk_mul_f32 v[34:35], v[34:35], v[162:163]
	v_cvt_pk_bf16_f32 v44, v40, v41
	v_cvt_pk_bf16_f32 v45, v42, v43
	v_cvt_pk_bf16_f32 v46, v32, v33
	v_cvt_pk_bf16_f32 v47, v34, v35
	v_lshl_add_u64 v[118:119], v[118:119], 0, v[120:121]
	global_store_dwordx4 v[118:119], v[44:47], off
	s_waitcnt lgkmcnt(0)
; __device__ __forceinline__ unsigned pk2(float lo, float hi) { unsigned r; asm volatile("v_cvt_pk_bf16_f32 %0, %1, %2" : "=v"(r) : "v"(lo), "v"(hi)); return r; }
; __device__ __forceinline__ unsigned pk2(float lo, float hi) { return f2bf(lo) | (f2bf(hi) << 16); }
; #define G_WAIT_V(n) asm volatile("s_waitcnt vmcnt(" #n ")" ::: "memory")
; #define G_BAR __builtin_amdgcn_s_barrier()
;     ...
;     G_WAIT_V(0);
;     if (wr == 0) G_BAR;
;     G_BAR;
;     __device__ __forceinline__ void epi(const f32x4 (&acc)[2][2][4][2], const Unit& u, int wr, int wc, int fr, int fq) const {
;     ...
;                 const int row = row0 + ai * 128 + m * 16; const float rs = rs_lds[((u.pm >> 3) & 1) * 256 + (row & 255)];
;                 const float rs2 = rs * -1.4426950408889634f, rsq = rs * rs;
;                 f32x2 v[4];
; #pragma unroll
;                 for (int n = 0; n < 2; ++n)
; #pragma unroll
;                     for (int jp = 0; jp < 2; ++jp) {
;                         const f32x2 gg = (f32x2){acc[ai][0][m][n][2 * jp], acc[ai][0][m][n][2 * jp + 1]}, uu = (f32x2){acc[ai][1][m][n][2 * jp], acc[ai][1][m][n][2 * jp + 1]};
;                         const f32x2 t = gg * rs2; f32x2 e; e.x = __builtin_amdgcn_exp2f(t.x); e.y = __builtin_amdgcn_exp2f(t.y);
;                         const f32x2 d = e + 1.0f; f32x2 r; r.x = __builtin_amdgcn_rcpf(d.x); r.y = __builtin_amdgcn_rcpf(d.y);
;                         v[n * 2 + jp] = (gg * uu) * (r * rsq);
;                     }
;                 u32x4 w; w.x = pk2(v[0].x, v[0].y); w.y = pk2(v[1].x, v[1].y); w.z = pk2(v[2].x, v[2].y); w.w = pk2(v[3].x, v[3].y);
;                 *(u32x4*)(H + (size_t)row * FF + col0) = w;
	v_mul_f32_e32 v144, 0xbfb8aa3b, v143
	v_mul_f32_e32 v164, v143, v143
	ds_read_b32 v143, v142 offset:704
	v_pk_mul_f32 v[160:161], v[24:25], v[144:145] op_sel_hi:[1,0]
	v_pk_mul_f32 v[162:163], v[26:27], v[144:145] op_sel_hi:[1,0]
	v_exp_f32_e32 v160, v160
	v_exp_f32_e32 v161, v161
	v_exp_f32_e32 v162, v162
	v_exp_f32_e32 v163, v163
	v_pk_mul_f32 v[24:25], v[24:25], v[28:29]
	v_pk_add_f32 v[160:161], v[160:161], 1.0 op_sel_hi:[1,0]
	v_pk_mul_f32 v[26:27], v[26:27], v[30:31]
	v_pk_add_f32 v[162:163], v[162:163], 1.0 op_sel_hi:[1,0]
	v_rcp_f32_e32 v160, v160
	v_rcp_f32_e32 v161, v161
	v_rcp_f32_e32 v162, v162
	v_rcp_f32_e32 v163, v163
	v_pk_mul_f32 v[160:161], v[164:165], v[160:161] op_sel_hi:[0,1]
	v_pk_mul_f32 v[24:25], v[24:25], v[160:161]
	v_pk_mul_f32 v[162:163], v[164:165], v[162:163] op_sel_hi:[0,1]
	v_pk_mul_f32 v[26:27], v[26:27], v[162:163]
	v_pk_mul_f32 v[160:161], v[16:17], v[144:145] op_sel_hi:[1,0]
	v_pk_mul_f32 v[162:163], v[18:19], v[144:145] op_sel_hi:[1,0]
	v_exp_f32_e32 v160, v160
	v_exp_f32_e32 v161, v161
	v_exp_f32_e32 v162, v162
	v_exp_f32_e32 v163, v163
	v_pk_mul_f32 v[16:17], v[16:17], v[20:21]
	v_pk_add_f32 v[160:161], v[160:161], 1.0 op_sel_hi:[1,0]
	v_pk_mul_f32 v[18:19], v[18:19], v[22:23]
	v_pk_add_f32 v[162:163], v[162:163], 1.0 op_sel_hi:[1,0]
	v_rcp_f32_e32 v160, v160
	v_rcp_f32_e32 v161, v161
	v_rcp_f32_e32 v162, v162
	v_rcp_f32_e32 v163, v163
	v_pk_mul_f32 v[160:161], v[164:165], v[160:161] op_sel_hi:[0,1]
	v_pk_mul_f32 v[16:17], v[16:17], v[160:161]
	v_pk_mul_f32 v[162:163], v[164:165], v[162:163] op_sel_hi:[0,1]
	v_pk_mul_f32 v[18:19], v[18:19], v[162:163]
	v_cvt_pk_bf16_f32 v28, v24, v25
	v_cvt_pk_bf16_f32 v29, v26, v27
	v_cvt_pk_bf16_f32 v30, v16, v17
	v_cvt_pk_bf16_f32 v31, v18, v19
	v_lshl_add_u64 v[118:119], v[118:119], 0, v[120:121]
	global_store_dwordx4 v[118:119], v[28:31], off
	s_waitcnt lgkmcnt(0)
	v_mul_f32_e32 v144, 0xbfb8aa3b, v143
	v_mul_f32_e32 v164, v143, v143
	v_pk_mul_f32 v[160:161], v[8:9], v[144:145] op_sel_hi:[1,0]
	v_pk_mul_f32 v[162:163], v[10:11], v[144:145] op_sel_hi:[1,0]
	v_exp_f32_e32 v160, v160
	v_exp_f32_e32 v161, v161
	v_exp_f32_e32 v162, v162
	v_exp_f32_e32 v163, v163
	v_pk_mul_f32 v[8:9], v[8:9], v[12:13]
	v_pk_add_f32 v[160:161], v[160:161], 1.0 op_sel_hi:[1,0]
	v_pk_mul_f32 v[10:11], v[10:11], v[14:15]
	v_pk_add_f32 v[162:163], v[162:163], 1.0 op_sel_hi:[1,0]
	v_rcp_f32_e32 v160, v160
	v_rcp_f32_e32 v161, v161
	v_rcp_f32_e32 v162, v162
	v_rcp_f32_e32 v163, v163
	v_pk_mul_f32 v[160:161], v[164:165], v[160:161] op_sel_hi:[0,1]
	v_pk_mul_f32 v[8:9], v[8:9], v[160:161]
	v_pk_mul_f32 v[162:163], v[164:165], v[162:163] op_sel_hi:[0,1]
	v_pk_mul_f32 v[10:11], v[10:11], v[162:163]
	v_pk_mul_f32 v[160:161], v[0:1], v[144:145] op_sel_hi:[1,0]
	v_pk_mul_f32 v[162:163], v[2:3], v[144:145] op_sel_hi:[1,0]
	v_exp_f32_e32 v160, v160
	v_exp_f32_e32 v161, v161
	v_exp_f32_e32 v162, v162
	v_exp_f32_e32 v163, v163
	v_pk_mul_f32 v[0:1], v[0:1], v[4:5]
	v_pk_add_f32 v[160:161], v[160:161], 1.0 op_sel_hi:[1,0]
	v_pk_mul_f32 v[2:3], v[2:3], v[6:7]
	v_pk_add_f32 v[162:163], v[162:163], 1.0 op_sel_hi:[1,0]
	v_rcp_f32_e32 v160, v160
	v_rcp_f32_e32 v161, v161
	v_rcp_f32_e32 v162, v162
	v_rcp_f32_e32 v163, v163
	v_pk_mul_f32 v[160:161], v[164:165], v[160:161] op_sel_hi:[0,1]
	v_pk_mul_f32 v[0:1], v[0:1], v[160:161]
	v_pk_mul_f32 v[162:163], v[164:165], v[162:163] op_sel_hi:[0,1]
	v_pk_mul_f32 v[2:3], v[2:3], v[162:163]
	v_cvt_pk_bf16_f32 v12, v8, v9
	v_cvt_pk_bf16_f32 v13, v10, v11
	v_cvt_pk_bf16_f32 v14, v0, v1
	v_cvt_pk_bf16_f32 v15, v2, v3
	v_lshl_add_u64 v[118:119], v[118:119], 0, v[120:121]
	global_store_dwordx4 v[118:119], v[12:15], off
	s_mov_b64 s[28:29], s[22:23]
	s_mov_b64 s[26:27], s[20:21]
	s_and_b64 vcc, exec, s[14:15]
	s_cbranch_vccz .LBB0_229
	s_waitcnt vmcnt(8)
	s_cmpk_gt_u32 s38, 0xff
	s_cbranch_scc1 .LBB0_236
	s_barrier

; #define G_WAIT_V(n) asm volatile("s_waitcnt vmcnt(" #n ")" ::: "memory")
; #define G_BAR __builtin_amdgcn_s_barrier()
;     ...
;     G_WAIT_V(0);
;     if (wr == 0) G_BAR;
;     G_BAR;
.LBB0_374:
	s_waitcnt vmcnt(16)
	s_cmpk_gt_u32 s39, 0xff
	s_cbranch_scc1 .LBB0_376
	s_barrier
